# accumulator zeroing between GEMM units: packed moves (64 per wave instead of 128)
# speedup vs baseline: 1.0012x; 1.0009x over previous
.LBB0_627:
	s_ashr_i32 s15, s14, 31
	s_lshl_b64 s[16:17], s[14:15], 19
	s_add_u32 s16, s28, s16
	s_addc_u32 s17, s29, s17
	s_and_b64 s[18:19], s[34:35], exec
	s_cselect_b32 s15, s17, s31
	s_cselect_b32 s48, s16, s30
	s_ashr_i32 s13, s12, 31
	s_lshl_b64 s[18:19], s[12:13], 19
	s_add_u32 s18, s6, s18
	s_addc_u32 s19, s7, s19
	s_and_b64 s[38:39], s[34:35], exec
	s_cselect_b32 s13, s19, s37
	s_cselect_b32 s49, s18, s36
	s_add_u32 s30, s30, 0x40080
	s_addc_u32 s31, s31, 0
	s_add_u32 s50, s36, 0x100
	v_mov_b32_e32 v2, 0
	s_addc_u32 s51, s37, 0
	s_mov_b32 s52, -2
	v_mov_b32_e32 v3, v2
	v_pk_mov_b32 v[4:5], v[2:3], v[2:3]
	v_pk_mov_b32 v[6:7], v[2:3], v[2:3]
	v_pk_mov_b32 v[8:9], v[2:3], v[2:3]
	v_pk_mov_b32 v[10:11], v[2:3], v[2:3]
	v_pk_mov_b32 v[12:13], v[2:3], v[2:3]
	v_pk_mov_b32 v[14:15], v[2:3], v[2:3]
	v_pk_mov_b32 v[16:17], v[2:3], v[2:3]
	v_pk_mov_b32 v[18:19], v[2:3], v[2:3]
	v_pk_mov_b32 v[20:21], v[2:3], v[2:3]
	v_pk_mov_b32 v[22:23], v[2:3], v[2:3]
	v_pk_mov_b32 v[24:25], v[2:3], v[2:3]
	v_pk_mov_b32 v[26:27], v[2:3], v[2:3]
	v_pk_mov_b32 v[28:29], v[2:3], v[2:3]
	v_pk_mov_b32 v[30:31], v[2:3], v[2:3]
	v_pk_mov_b32 v[32:33], v[2:3], v[2:3]
	v_pk_mov_b32 v[34:35], v[2:3], v[2:3]
	v_pk_mov_b32 v[36:37], v[2:3], v[2:3]
	v_pk_mov_b32 v[38:39], v[2:3], v[2:3]
	v_pk_mov_b32 v[40:41], v[2:3], v[2:3]
	v_pk_mov_b32 v[42:43], v[2:3], v[2:3]
	v_pk_mov_b32 v[44:45], v[2:3], v[2:3]
	v_pk_mov_b32 v[46:47], v[2:3], v[2:3]
	v_pk_mov_b32 v[48:49], v[2:3], v[2:3]
	v_pk_mov_b32 v[50:51], v[2:3], v[2:3]
	v_pk_mov_b32 v[52:53], v[2:3], v[2:3]
	v_pk_mov_b32 v[54:55], v[2:3], v[2:3]
	v_pk_mov_b32 v[56:57], v[2:3], v[2:3]
	v_pk_mov_b32 v[58:59], v[2:3], v[2:3]
	v_pk_mov_b32 v[60:61], v[2:3], v[2:3]
	v_pk_mov_b32 v[62:63], v[2:3], v[2:3]
	v_pk_mov_b32 v[64:65], v[2:3], v[2:3]
	v_pk_mov_b32 v[66:67], v[2:3], v[2:3]
	v_pk_mov_b32 v[68:69], v[2:3], v[2:3]
	v_pk_mov_b32 v[70:71], v[2:3], v[2:3]
	v_pk_mov_b32 v[72:73], v[2:3], v[2:3]
	v_pk_mov_b32 v[74:75], v[2:3], v[2:3]
	v_pk_mov_b32 v[76:77], v[2:3], v[2:3]
	v_pk_mov_b32 v[78:79], v[2:3], v[2:3]
	v_pk_mov_b32 v[80:81], v[2:3], v[2:3]
	v_pk_mov_b32 v[82:83], v[2:3], v[2:3]
	v_pk_mov_b32 v[84:85], v[2:3], v[2:3]
	v_pk_mov_b32 v[86:87], v[2:3], v[2:3]
	v_pk_mov_b32 v[88:89], v[2:3], v[2:3]
	v_pk_mov_b32 v[90:91], v[2:3], v[2:3]
	v_pk_mov_b32 v[92:93], v[2:3], v[2:3]
	v_pk_mov_b32 v[94:95], v[2:3], v[2:3]
	v_pk_mov_b32 v[96:97], v[2:3], v[2:3]
	v_pk_mov_b32 v[98:99], v[2:3], v[2:3]
	v_pk_mov_b32 v[100:101], v[2:3], v[2:3]
	v_pk_mov_b32 v[102:103], v[2:3], v[2:3]
	v_pk_mov_b32 v[104:105], v[2:3], v[2:3]
	v_pk_mov_b32 v[106:107], v[2:3], v[2:3]
	v_pk_mov_b32 v[108:109], v[2:3], v[2:3]
	v_pk_mov_b32 v[110:111], v[2:3], v[2:3]
	v_pk_mov_b32 v[112:113], v[2:3], v[2:3]
	v_pk_mov_b32 v[114:115], v[2:3], v[2:3]
	v_pk_mov_b32 v[116:117], v[2:3], v[2:3]
	v_pk_mov_b32 v[118:119], v[2:3], v[2:3]
	v_pk_mov_b32 v[120:121], v[2:3], v[2:3]
	v_pk_mov_b32 v[122:123], v[2:3], v[2:3]
	v_pk_mov_b32 v[124:125], v[2:3], v[2:3]
	v_pk_mov_b32 v[126:127], v[2:3], v[2:3]
	v_pk_mov_b32 v[128:129], v[2:3], v[2:3]

.LBB0_681:
	s_add_u32 s12, s12, 0x80
	s_addc_u32 s13, s13, 0
	s_add_u32 s40, s40, 0x100
	v_mov_b32_e32 v2, 0
	s_addc_u32 s41, s41, 0
	s_mov_b32 s38, 0
	v_mov_b32_e32 v3, v2
	v_pk_mov_b32 v[4:5], v[2:3], v[2:3]
	v_pk_mov_b32 v[6:7], v[2:3], v[2:3]
	v_pk_mov_b32 v[8:9], v[2:3], v[2:3]
	v_pk_mov_b32 v[10:11], v[2:3], v[2:3]
	v_pk_mov_b32 v[12:13], v[2:3], v[2:3]
	v_pk_mov_b32 v[14:15], v[2:3], v[2:3]
	v_pk_mov_b32 v[16:17], v[2:3], v[2:3]
	v_pk_mov_b32 v[18:19], v[2:3], v[2:3]
	v_pk_mov_b32 v[20:21], v[2:3], v[2:3]
	v_pk_mov_b32 v[22:23], v[2:3], v[2:3]
	v_pk_mov_b32 v[24:25], v[2:3], v[2:3]
	v_pk_mov_b32 v[26:27], v[2:3], v[2:3]
	v_pk_mov_b32 v[28:29], v[2:3], v[2:3]
	v_pk_mov_b32 v[30:31], v[2:3], v[2:3]
	v_pk_mov_b32 v[32:33], v[2:3], v[2:3]
	v_pk_mov_b32 v[34:35], v[2:3], v[2:3]
	v_pk_mov_b32 v[36:37], v[2:3], v[2:3]
	v_pk_mov_b32 v[42:43], v[2:3], v[2:3]
	v_pk_mov_b32 v[44:45], v[2:3], v[2:3]
	v_pk_mov_b32 v[58:59], v[2:3], v[2:3]
	v_pk_mov_b32 v[60:61], v[2:3], v[2:3]
	v_pk_mov_b32 v[62:63], v[2:3], v[2:3]
	v_pk_mov_b32 v[64:65], v[2:3], v[2:3]
	v_pk_mov_b32 v[66:67], v[2:3], v[2:3]
	v_pk_mov_b32 v[68:69], v[2:3], v[2:3]
	v_pk_mov_b32 v[70:71], v[2:3], v[2:3]
	v_pk_mov_b32 v[72:73], v[2:3], v[2:3]
	v_pk_mov_b32 v[74:75], v[2:3], v[2:3]
	v_pk_mov_b32 v[76:77], v[2:3], v[2:3]
	v_pk_mov_b32 v[78:79], v[2:3], v[2:3]
	v_pk_mov_b32 v[80:81], v[2:3], v[2:3]
	v_pk_mov_b32 v[82:83], v[2:3], v[2:3]
	v_pk_mov_b32 v[84:85], v[2:3], v[2:3]
	v_pk_mov_b32 v[86:87], v[2:3], v[2:3]
	v_pk_mov_b32 v[88:89], v[2:3], v[2:3]
	v_pk_mov_b32 v[90:91], v[2:3], v[2:3]
	v_pk_mov_b32 v[92:93], v[2:3], v[2:3]
	v_pk_mov_b32 v[94:95], v[2:3], v[2:3]
	v_pk_mov_b32 v[96:97], v[2:3], v[2:3]
	v_pk_mov_b32 v[98:99], v[2:3], v[2:3]
	v_pk_mov_b32 v[100:101], v[2:3], v[2:3]
	v_pk_mov_b32 v[102:103], v[2:3], v[2:3]
	v_pk_mov_b32 v[104:105], v[2:3], v[2:3]
	v_pk_mov_b32 v[106:107], v[2:3], v[2:3]
	v_pk_mov_b32 v[108:109], v[2:3], v[2:3]
	v_pk_mov_b32 v[110:111], v[2:3], v[2:3]
	v_pk_mov_b32 v[112:113], v[2:3], v[2:3]
	v_pk_mov_b32 v[114:115], v[2:3], v[2:3]
	v_pk_mov_b32 v[116:117], v[2:3], v[2:3]
	v_pk_mov_b32 v[118:119], v[2:3], v[2:3]
	v_pk_mov_b32 v[120:121], v[2:3], v[2:3]
	v_pk_mov_b32 v[122:123], v[2:3], v[2:3]
	v_pk_mov_b32 v[124:125], v[2:3], v[2:3]
	v_pk_mov_b32 v[126:127], v[2:3], v[2:3]
	v_pk_mov_b32 v[128:129], v[2:3], v[2:3]
	v_pk_mov_b32 v[130:131], v[2:3], v[2:3]
	v_pk_mov_b32 v[132:133], v[2:3], v[2:3]
	v_pk_mov_b32 v[134:135], v[2:3], v[2:3]
	v_pk_mov_b32 v[136:137], v[2:3], v[2:3]
	v_pk_mov_b32 v[138:139], v[2:3], v[2:3]
	v_pk_mov_b32 v[140:141], v[2:3], v[2:3]
	v_pk_mov_b32 v[142:143], v[2:3], v[2:3]
	v_pk_mov_b32 v[144:145], v[2:3], v[2:3]

.LBB0_811:
	s_ashr_i32 s17, s16, 31
	s_lshl_b64 s[18:19], s[16:17], 19
	s_add_u32 s18, s28, s18
	s_addc_u32 s19, s29, s19
	s_and_b64 s[26:27], s[34:35], exec
	s_cselect_b32 s17, s19, s37
	s_cselect_b32 s50, s18, s36
	s_ashr_i32 s15, s14, 31
	s_lshl_b64 s[26:27], s[14:15], 19
	s_add_u32 s26, s0, s26
	s_addc_u32 s27, s6, s27
	s_and_b64 s[40:41], s[34:35], exec
	s_cselect_b32 s15, s27, s39
	s_cselect_b32 s51, s26, s38
	s_add_u32 s36, s36, 0x40080
	s_addc_u32 s37, s37, 0
	s_add_u32 s52, s38, 0x100
	v_mov_b32_e32 v2, 0
	s_addc_u32 s53, s39, 0
	s_mov_b32 s54, -2
	v_mov_b32_e32 v3, v2
	v_pk_mov_b32 v[4:5], v[2:3], v[2:3]
	v_pk_mov_b32 v[6:7], v[2:3], v[2:3]
	v_pk_mov_b32 v[8:9], v[2:3], v[2:3]
	v_pk_mov_b32 v[10:11], v[2:3], v[2:3]
	v_pk_mov_b32 v[12:13], v[2:3], v[2:3]
	v_pk_mov_b32 v[14:15], v[2:3], v[2:3]
	v_pk_mov_b32 v[16:17], v[2:3], v[2:3]
	v_pk_mov_b32 v[18:19], v[2:3], v[2:3]
	v_pk_mov_b32 v[20:21], v[2:3], v[2:3]
	v_pk_mov_b32 v[22:23], v[2:3], v[2:3]
	v_pk_mov_b32 v[24:25], v[2:3], v[2:3]
	v_pk_mov_b32 v[26:27], v[2:3], v[2:3]
	v_pk_mov_b32 v[28:29], v[2:3], v[2:3]
	v_pk_mov_b32 v[30:31], v[2:3], v[2:3]
	v_pk_mov_b32 v[32:33], v[2:3], v[2:3]
	v_pk_mov_b32 v[34:35], v[2:3], v[2:3]
	v_pk_mov_b32 v[36:37], v[2:3], v[2:3]
	v_pk_mov_b32 v[38:39], v[2:3], v[2:3]
	v_pk_mov_b32 v[40:41], v[2:3], v[2:3]
	v_pk_mov_b32 v[42:43], v[2:3], v[2:3]
	v_pk_mov_b32 v[44:45], v[2:3], v[2:3]
	v_pk_mov_b32 v[46:47], v[2:3], v[2:3]
	v_pk_mov_b32 v[48:49], v[2:3], v[2:3]
	v_pk_mov_b32 v[50:51], v[2:3], v[2:3]
	v_pk_mov_b32 v[52:53], v[2:3], v[2:3]
	v_pk_mov_b32 v[54:55], v[2:3], v[2:3]
	v_pk_mov_b32 v[56:57], v[2:3], v[2:3]
	v_pk_mov_b32 v[58:59], v[2:3], v[2:3]
	v_pk_mov_b32 v[60:61], v[2:3], v[2:3]
	v_pk_mov_b32 v[62:63], v[2:3], v[2:3]
	v_pk_mov_b32 v[64:65], v[2:3], v[2:3]
	v_pk_mov_b32 v[66:67], v[2:3], v[2:3]
	v_pk_mov_b32 v[68:69], v[2:3], v[2:3]
	v_pk_mov_b32 v[70:71], v[2:3], v[2:3]
	v_pk_mov_b32 v[72:73], v[2:3], v[2:3]
	v_pk_mov_b32 v[74:75], v[2:3], v[2:3]
	v_pk_mov_b32 v[76:77], v[2:3], v[2:3]
	v_pk_mov_b32 v[78:79], v[2:3], v[2:3]
	v_pk_mov_b32 v[80:81], v[2:3], v[2:3]
	v_pk_mov_b32 v[82:83], v[2:3], v[2:3]
	v_pk_mov_b32 v[84:85], v[2:3], v[2:3]
	v_pk_mov_b32 v[86:87], v[2:3], v[2:3]
	v_pk_mov_b32 v[88:89], v[2:3], v[2:3]
	v_pk_mov_b32 v[90:91], v[2:3], v[2:3]
	v_pk_mov_b32 v[92:93], v[2:3], v[2:3]
	v_pk_mov_b32 v[94:95], v[2:3], v[2:3]
	v_pk_mov_b32 v[96:97], v[2:3], v[2:3]
	v_pk_mov_b32 v[98:99], v[2:3], v[2:3]
	v_pk_mov_b32 v[100:101], v[2:3], v[2:3]
	v_pk_mov_b32 v[102:103], v[2:3], v[2:3]
	v_pk_mov_b32 v[104:105], v[2:3], v[2:3]
	v_pk_mov_b32 v[106:107], v[2:3], v[2:3]
	v_pk_mov_b32 v[108:109], v[2:3], v[2:3]
	v_pk_mov_b32 v[110:111], v[2:3], v[2:3]
	v_pk_mov_b32 v[112:113], v[2:3], v[2:3]
	v_pk_mov_b32 v[114:115], v[2:3], v[2:3]
	v_pk_mov_b32 v[116:117], v[2:3], v[2:3]
	v_pk_mov_b32 v[118:119], v[2:3], v[2:3]
	v_pk_mov_b32 v[120:121], v[2:3], v[2:3]
	v_pk_mov_b32 v[122:123], v[2:3], v[2:3]
	v_pk_mov_b32 v[124:125], v[2:3], v[2:3]
	v_pk_mov_b32 v[126:127], v[2:3], v[2:3]
	v_pk_mov_b32 v[128:129], v[2:3], v[2:3]
